# v39 + M4 kv_b epilogue: the eight per-row ssq_kp loads issued together at the head of the second row loop (7 serial round trips per tile removed)
# baseline (speedup 1.0000x reference)
; __device__ __forceinline__ unsigned cvt_pk_bf16(float lo, float hi) { unsigned r; asm volatile("v_cvt_pk_bf16_f32 %0, %1, %2" : "=v"(r) : "v"(lo), "v"(hi)); return r; }
; #define PG8_LAS __attribute__((address_space(3)))
;     __device__ __forceinline__ void operator()(const f32x4 (&acc)[2][2][4][2], const Unit& u, int wr, int wc, int fr, int fq) const {
;     ...
; #pragma unroll
;         for (int ai = 0; ai < 2; ++ai)
; #pragma unroll
;             for (int m = 0; m < 4; ++m) { const int row = row0 + ai * HALF + m * 16;
;                 const f32x4 p = *(const PG8_LAS f32x4*)(scr + (ai * HALF + rowl0 + m * 16) * 4);
;                 const float rinv = __builtin_amdgcn_rsqf((((p[0] + p[1]) + (p[2] + p[3])) + ssq_kp[row]) * (1.f / QKD) + EPS), ks = rl[ai][m] * rinv;
;                 bf16_t* kvp = KV + (size_t)row * (NH * 256) + h * 256 + colk;
;                 { const f32x4 k0 = acc[ai][0][m][0] * ks * g0, k1 = acc[ai][0][m][1] * ks * g1;
;                   u32x4 w; w.x = cvt_pk_bf16(k0[0], k0[1]); w.y = cvt_pk_bf16(k0[2], k0[3]); w.z = cvt_pk_bf16(k1[0], k1[1]); w.w = cvt_pk_bf16(k1[2], k1[3]); *(u32x4*)kvp = w; }
;                 { const f32x4 v0 = acc[ai][1][m][0] * rl[ai][m], v1 = acc[ai][1][m][1] * rl[ai][m];
;                   u32x4 w; w.x = cvt_pk_bf16(v0[0], v0[1]); w.y = cvt_pk_bf16(v0[2], v0[3]); w.z = cvt_pk_bf16(v1[0], v1[1]); w.w = cvt_pk_bf16(v1[2], v1[3]); *(u32x4*)(kvp + 128) = w; }
;                 const float* kp = QK + (size_t)row * NQKVA + (QLORA + KVLORA) + dA;
;                 const f32x2 ya = *(const f32x2*)kp * rinv * ga, yb = *(const f32x2*)(kp + 16) * rinv * gb;
;                 f32x2 cs = (f32x2){1.f, 1.f}, sn = (f32x2){0.f, 0.f};
;                 if (row < MLAT) { const int s = row & (SEQ - 1), pos = wc < 2 ? (s >> 6) : (s & 63); cs = *(const f32x2*)(rope + pos * 16 + ff); sn = *(const f32x2*)(rope + 1024 + pos * 16 + ff); }
;                 const f32x2 za = ya * cs - yb * sn, zb = yb * cs + ya * sn;
;                 bf16_t* pe = KPE + (size_t)row * (NH * QKR) + h * QKR + dA;
;                 *(unsigned*)pe = cvt_pk_bf16(za.x, za.y); *(unsigned*)(pe + 16) = cvt_pk_bf16(zb.x, zb.y); }
.LBB0_1356:
	s_or_b64 exec, exec, s[36:37]
	s_waitcnt lgkmcnt(0)
	s_barrier
	v_lshl_add_u64 v[178:179], v[166:167], 2, s[20:21]
	s_waitcnt lgkmcnt(0)
	global_load_dwordx4 v[64:67], v[148:149], off offset:16
	global_load_dwordx4 v[68:71], v[148:149], off
	global_load_dwordx2 v[156:157], v[150:151], off offset:512
	global_load_dwordx2 v[158:159], v[150:151], off offset:576
	global_load_dword v244, v[178:179], off offset:64
	global_load_dword v243, v[178:179], off offset:128
	global_load_dword v242, v[178:179], off offset:192
	global_load_dword v241, v[178:179], off offset:512
	global_load_dword v240, v[178:179], off offset:576
	global_load_dword v239, v[178:179], off offset:640
	global_load_dword v238, v[178:179], off offset:704
	global_load_dword v165, v[178:179], off
	v_add_u32_e32 v163, 0, v199
	v_add_u32_e32 v163, 0x20000, v163
	ds_read_b128 v[202:205], v163
	s_lshl_b32 s36, s38, 8
	v_lshlrev_b64 v[176:177], 12, v[166:167]
	s_ashr_i32 s37, s36, 31
	v_lshl_add_u64 v[176:177], s[14:15], 0, v[176:177]
	s_waitcnt lgkmcnt(0)
	v_mov_b32_e32 v174, v203
	v_mov_b32_e32 v175, v204
	v_mov_b32_e32 v203, v205
	v_pk_add_f32 v[174:175], v[174:175], v[202:203]
	v_lshl_add_u64 v[176:177], s[36:37], 1, v[176:177]
	v_add_f32_e32 v163, v174, v175
	v_lshl_add_u64 v[176:177], v[176:177], 0, v[172:173]
	v_mov_b32_e32 v185, v184
	v_pk_mul_f32 v[124:125], v[124:125], v[184:185]
	v_lshrrev_b32_e32 v161, 6, v166
	v_cmp_gt_i32_e32 vcc, s83, v166
	s_waitcnt vmcnt(0)
	v_add_f32_e32 v163, v165, v163
	v_fmamk_f32 v163, v163, 0x3baaaaab, v189
	v_rsq_f32_e32 v186, v163
	s_nop 0
	v_mul_f32_e32 v174, v184, v186
	v_pk_mul_f32 v[132:133], v[132:133], v[174:175] op_sel_hi:[1,0]
	v_pk_mul_f32 v[134:135], v[134:135], v[174:175] op_sel_hi:[1,0]
	v_pk_mul_f32 v[128:129], v[128:129], v[174:175] op_sel_hi:[1,0]
	v_pk_mul_f32 v[130:131], v[130:131], v[174:175] op_sel_hi:[1,0]
	v_pk_mul_f32 v[134:135], v[70:71], v[134:135]
	v_pk_mul_f32 v[132:133], v[68:69], v[132:133]
	v_pk_mul_f32 v[174:175], v[66:67], v[130:131]
	v_pk_mul_f32 v[130:131], v[64:65], v[128:129]
	v_cvt_pk_bf16_f32 v128, v132, v133
	v_cvt_pk_bf16_f32 v129, v134, v135
	s_nop 0
	v_cvt_pk_bf16_f32 v130, v130, v131
	v_cvt_pk_bf16_f32 v131, v174, v175
	global_store_dwordx4 v[176:177], v[128:131], off
	s_nop 1
	v_mov_b32_e32 v128, v184
	v_mov_b32_e32 v129, v184
	v_pk_mul_f32 v[126:127], v[126:127], v[128:129]
	v_pk_mul_f32 v[128:129], v[122:123], v[128:129]
	v_pk_mul_f32 v[122:123], v[120:121], v[184:185]
	v_cvt_pk_bf16_f32 v120, v124, v125
	v_cvt_pk_bf16_f32 v121, v126, v127
	v_mov_b32_e32 v124, 0
	v_cvt_pk_bf16_f32 v122, v122, v123
	v_cvt_pk_bf16_f32 v123, v128, v129
	global_store_dwordx4 v[176:177], v[120:123], off offset:256
	v_mov_b32_e32 v128, 1.0
	v_mov_b32_e32 v129, 1.0
	v_mad_i64_i32 v[120:121], s[40:41], v166, s89, v[154:155]
	global_load_dwordx2 v[126:127], v[120:121], off offset:2560
	s_nop 0
	global_load_dwordx2 v[120:121], v[120:121], off offset:2624
	v_mov_b32_e32 v122, 1.0
	v_mov_b32_e32 v130, 0
	v_mov_b32_e32 v131, 0
	s_and_saveexec_b64 s[40:41], vcc
	s_cbranch_execz .LBB0_1358
	v_cndmask_b32_e64 v123, v145, v161, s[8:9]
	v_lshlrev_b32_e32 v123, 6, v123
	v_and_b32_e32 v128, 0xfc0, v123
	v_mov_b32_e32 v129, v173
	v_lshl_add_u64 v[130:131], v[146:147], 0, v[128:129]
	v_lshl_add_u64 v[132:133], v[152:153], 0, v[128:129]
	global_load_dwordx2 v[128:129], v[130:131], off
	s_nop 0
	global_load_dwordx2 v[130:131], v[132:133], off
.LBB0_1358:
	s_or_b64 exec, exec, s[40:41]
	s_waitcnt vmcnt(0)
	v_pk_mul_f32 v[120:121], v[186:187], v[120:121] op_sel_hi:[0,1]
	v_pk_mul_f32 v[126:127], v[186:187], v[126:127] op_sel_hi:[0,1]
	v_pk_mul_f32 v[120:121], v[158:159], v[120:121]
	v_pk_mul_f32 v[126:127], v[156:157], v[126:127]
	v_pk_mul_f32 v[132:133], v[120:121], v[130:131]
	s_lshl_b32 s38, s38, 6
	v_pk_fma_f32 v[132:133], v[126:127], v[128:129], v[132:133] neg_lo:[0,0,1] neg_hi:[0,0,1]
	v_pk_mul_f32 v[126:127], v[126:127], v[130:131]
	s_ashr_i32 s39, s38, 31
	v_pk_fma_f32 v[126:127], v[120:121], v[128:129], v[126:127]
	v_lshlrev_b64 v[120:121], 10, v[166:167]
	v_lshl_add_u64 v[120:121], s[16:17], 0, v[120:121]
	v_lshl_add_u64 v[128:129], s[38:39], 1, v[120:121]
	v_lshlrev_b32_e32 v120, 1, v144
	v_mov_b32_e32 v121, v173
	v_lshl_add_u64 v[128:129], v[128:129], 0, v[120:121]
	v_cvt_pk_bf16_f32 v123, v132, v133
	s_add_i32 s27, 0, 0x20000
	global_store_dword v[128:129], v123, off
	v_cvt_pk_bf16_f32 v123, v126, v127
	global_store_dword v[128:129], v123, off offset:32
	v_add_u32_e32 v129, s27, v199
	ds_read_b128 v[130:133], v129 offset:256
	v_or_b32_e32 v126, 16, v166
	v_ashrrev_i32_e32 v127, 31, v126
	v_mov_b32_e32 v183, v182
	v_pk_mul_f32 v[108:109], v[108:109], v[182:183]
	s_waitcnt lgkmcnt(0)
	v_mov_b32_e32 v134, v131
	v_mov_b32_e32 v135, v132
	v_mov_b32_e32 v131, v133
	v_pk_add_f32 v[130:131], v[134:135], v[130:131]
	v_lshlrev_b64 v[132:133], 12, v[126:127]
	v_add_f32_e32 v123, v130, v131
	v_lshl_add_u64 v[130:131], v[126:127], 2, s[20:21]
	s_nop 2
	v_mov_b32_e32 v125, v244
	v_lshl_add_u64 v[132:133], s[14:15], 0, v[132:133]
	v_lshl_add_u64 v[132:133], s[36:37], 1, v[132:133]
	v_lshl_add_u64 v[132:133], v[132:133], 0, v[172:173]
	v_cmp_gt_i32_e32 vcc, s83, v126
	v_add_f32_e32 v123, v125, v123
	v_fmamk_f32 v123, v123, 0x3baaaaab, v189
	v_rsq_f32_e32 v128, v123
	v_mov_b32_e32 v123, 1.0
	v_mov_b32_e32 v125, 0
	v_mul_f32_e32 v130, v182, v128
	v_pk_mul_f32 v[116:117], v[116:117], v[130:131] op_sel_hi:[1,0]
	v_pk_mul_f32 v[118:119], v[118:119], v[130:131] op_sel_hi:[1,0]
	v_pk_mul_f32 v[112:113], v[112:113], v[130:131] op_sel_hi:[1,0]
	v_pk_mul_f32 v[114:115], v[114:115], v[130:131] op_sel_hi:[1,0]
	v_pk_mul_f32 v[118:119], v[70:71], v[118:119]
	v_pk_mul_f32 v[116:117], v[68:69], v[116:117]
	v_pk_mul_f32 v[130:131], v[66:67], v[114:115]
	v_pk_mul_f32 v[114:115], v[64:65], v[112:113]
	v_cvt_pk_bf16_f32 v112, v116, v117
	v_cvt_pk_bf16_f32 v113, v118, v119
	s_nop 0
	v_cvt_pk_bf16_f32 v114, v114, v115
	v_cvt_pk_bf16_f32 v115, v130, v131
	global_store_dwordx4 v[132:133], v[112:115], off
	s_nop 1
	v_mov_b32_e32 v112, v182
	v_mov_b32_e32 v113, v182
	v_pk_mul_f32 v[110:111], v[110:111], v[112:113]
	v_pk_mul_f32 v[112:113], v[106:107], v[112:113]
	v_pk_mul_f32 v[106:107], v[104:105], v[182:183]
	v_cvt_pk_bf16_f32 v104, v108, v109
	v_cvt_pk_bf16_f32 v105, v110, v111
	s_nop 0
	v_cvt_pk_bf16_f32 v106, v106, v107
	v_cvt_pk_bf16_f32 v107, v112, v113
	global_store_dwordx4 v[132:133], v[104:107], off offset:256
	s_nop 1
	v_mad_i64_i32 v[104:105], s[40:41], v126, s89, v[154:155]
	global_load_dwordx2 v[106:107], v[104:105], off offset:2560
	s_nop 0
	global_load_dwordx2 v[104:105], v[104:105], off offset:2624
	s_and_saveexec_b64 s[40:41], vcc
	s_cbranch_execz .LBB0_1360
	v_cndmask_b32_e64 v108, v126, v161, s[8:9]
	v_lshlrev_b32_e32 v108, 6, v108
	v_and_b32_e32 v108, 0xfc0, v108
	v_mov_b32_e32 v109, v173
	v_lshl_add_u64 v[110:111], v[146:147], 0, v[108:109]
	v_lshl_add_u64 v[108:109], v[152:153], 0, v[108:109]
	global_load_dwordx2 v[122:123], v[110:111], off
	global_load_dwordx2 v[124:125], v[108:109], off
; __device__ __forceinline__ unsigned cvt_pk_bf16(float lo, float hi) { unsigned r; asm volatile("v_cvt_pk_bf16_f32 %0, %1, %2" : "=v"(r) : "v"(lo), "v"(hi)); return r; }
; #define PG8_LAS __attribute__((address_space(3)))
;     __device__ __forceinline__ void operator()(const f32x4 (&acc)[2][2][4][2], const Unit& u, int wr, int wc, int fr, int fq) const {
;     ...
; #pragma unroll
;         for (int ai = 0; ai < 2; ++ai)
; #pragma unroll
;             for (int m = 0; m < 4; ++m) { const int row = row0 + ai * HALF + m * 16;
;                 const f32x4 p = *(const PG8_LAS f32x4*)(scr + (ai * HALF + rowl0 + m * 16) * 4);
;                 const float rinv = __builtin_amdgcn_rsqf((((p[0] + p[1]) + (p[2] + p[3])) + ssq_kp[row]) * (1.f / QKD) + EPS), ks = rl[ai][m] * rinv;
;                 bf16_t* kvp = KV + (size_t)row * (NH * 256) + h * 256 + colk;
;                 { const f32x4 k0 = acc[ai][0][m][0] * ks * g0, k1 = acc[ai][0][m][1] * ks * g1;
;                   u32x4 w; w.x = cvt_pk_bf16(k0[0], k0[1]); w.y = cvt_pk_bf16(k0[2], k0[3]); w.z = cvt_pk_bf16(k1[0], k1[1]); w.w = cvt_pk_bf16(k1[2], k1[3]); *(u32x4*)kvp = w; }
;                 { const f32x4 v0 = acc[ai][1][m][0] * rl[ai][m], v1 = acc[ai][1][m][1] * rl[ai][m];
;                   u32x4 w; w.x = cvt_pk_bf16(v0[0], v0[1]); w.y = cvt_pk_bf16(v0[2], v0[3]); w.z = cvt_pk_bf16(v1[0], v1[1]); w.w = cvt_pk_bf16(v1[2], v1[3]); *(u32x4*)(kvp + 128) = w; }
;                 const float* kp = QK + (size_t)row * NQKVA + (QLORA + KVLORA) + dA;
;                 const f32x2 ya = *(const f32x2*)kp * rinv * ga, yb = *(const f32x2*)(kp + 16) * rinv * gb;
;                 f32x2 cs = (f32x2){1.f, 1.f}, sn = (f32x2){0.f, 0.f};
;                 if (row < MLAT) { const int s = row & (SEQ - 1), pos = wc < 2 ? (s >> 6) : (s & 63); cs = *(const f32x2*)(rope + pos * 16 + ff); sn = *(const f32x2*)(rope + 1024 + pos * 16 + ff); }
;                 const f32x2 za = ya * cs - yb * sn, zb = yb * cs + ya * sn;
;                 bf16_t* pe = KPE + (size_t)row * (NH * QKR) + h * QKR + dA;
;                 *(unsigned*)pe = cvt_pk_bf16(za.x, za.y); *(unsigned*)(pe + 16) = cvt_pk_bf16(zb.x, zb.y); }
.LBB0_1360:
	s_or_b64 exec, exec, s[40:41]
	s_waitcnt vmcnt(0)
	v_pk_mul_f32 v[104:105], v[128:129], v[104:105] op_sel_hi:[0,1]
	v_pk_mul_f32 v[106:107], v[128:129], v[106:107] op_sel_hi:[0,1]
	v_pk_mul_f32 v[104:105], v[158:159], v[104:105]
	v_pk_mul_f32 v[106:107], v[156:157], v[106:107]
	v_pk_mul_f32 v[108:109], v[104:105], v[124:125]
	v_mov_b32_e32 v181, v180
	v_pk_fma_f32 v[108:109], v[106:107], v[122:123], v[108:109] neg_lo:[0,0,1] neg_hi:[0,0,1]
	v_pk_mul_f32 v[106:107], v[106:107], v[124:125]
	v_cvt_pk_bf16_f32 v108, v108, v109
	v_pk_mul_f32 v[92:93], v[92:93], v[180:181]
	v_pk_fma_f32 v[104:105], v[104:105], v[122:123], v[106:107]
	v_lshlrev_b64 v[106:107], 10, v[126:127]
	v_lshl_add_u64 v[106:107], s[16:17], 0, v[106:107]
	v_lshl_add_u64 v[106:107], s[38:39], 1, v[106:107]
	v_lshl_add_u64 v[106:107], v[106:107], 0, v[120:121]
	global_store_dword v[106:107], v108, off
	v_cvt_pk_bf16_f32 v104, v104, v105
	global_store_dword v[106:107], v104, off offset:32
	ds_read_b128 v[106:109], v129 offset:512
	v_or_b32_e32 v104, 32, v166
	v_ashrrev_i32_e32 v105, 31, v104
	v_cmp_gt_i32_e32 vcc, s83, v104
	s_waitcnt lgkmcnt(0)
	v_mov_b32_e32 v110, v107
	v_mov_b32_e32 v111, v108
	v_mov_b32_e32 v107, v109
	v_pk_add_f32 v[106:107], v[110:111], v[106:107]
	v_lshlrev_b64 v[110:111], 12, v[104:105]
	v_add_f32_e32 v108, v106, v107
	v_lshl_add_u64 v[106:107], v[104:105], 2, s[20:21]
	s_nop 2
	v_mov_b32_e32 v106, v243
	v_lshl_add_u64 v[110:111], s[14:15], 0, v[110:111]
	v_lshl_add_u64 v[110:111], s[36:37], 1, v[110:111]
	v_lshl_add_u64 v[110:111], v[110:111], 0, v[172:173]
	v_add_f32_e32 v106, v106, v108
	v_fmamk_f32 v106, v106, 0x3baaaaab, v189
	v_rsq_f32_e32 v106, v106
	s_nop 0
	v_mul_f32_e32 v108, v180, v106
	v_pk_mul_f32 v[100:101], v[100:101], v[108:109] op_sel_hi:[1,0]
	v_pk_mul_f32 v[102:103], v[102:103], v[108:109] op_sel_hi:[1,0]
	v_pk_mul_f32 v[96:97], v[96:97], v[108:109] op_sel_hi:[1,0]
	v_pk_mul_f32 v[98:99], v[98:99], v[108:109] op_sel_hi:[1,0]
	v_pk_mul_f32 v[102:103], v[70:71], v[102:103]
	v_pk_mul_f32 v[100:101], v[68:69], v[100:101]
	v_pk_mul_f32 v[108:109], v[66:67], v[98:99]
	v_pk_mul_f32 v[98:99], v[64:65], v[96:97]
	v_cvt_pk_bf16_f32 v96, v100, v101
	v_cvt_pk_bf16_f32 v97, v102, v103
	s_nop 0
	v_cvt_pk_bf16_f32 v98, v98, v99
	v_cvt_pk_bf16_f32 v99, v108, v109
	global_store_dwordx4 v[110:111], v[96:99], off
	s_nop 1
	v_mov_b32_e32 v96, v180
	v_mov_b32_e32 v97, v180
	v_pk_mul_f32 v[94:95], v[94:95], v[96:97]
	v_pk_mul_f32 v[96:97], v[90:91], v[96:97]
	v_pk_mul_f32 v[90:91], v[88:89], v[180:181]
	v_cvt_pk_bf16_f32 v88, v92, v93
	v_cvt_pk_bf16_f32 v89, v94, v95
	v_mov_b32_e32 v98, 0
	v_cvt_pk_bf16_f32 v90, v90, v91
	v_cvt_pk_bf16_f32 v91, v96, v97
	global_store_dwordx4 v[110:111], v[88:91], off offset:256
	v_mov_b32_e32 v96, 1.0
	v_mov_b32_e32 v97, 1.0
	v_mad_i64_i32 v[88:89], s[40:41], v104, s89, v[154:155]
	global_load_dwordx2 v[94:95], v[88:89], off offset:2560
	global_load_dwordx2 v[92:93], v[88:89], off offset:2624
	v_mov_b32_e32 v90, 0
	v_mov_b32_e32 v88, 1.0
	v_mov_b32_e32 v99, 0
	s_and_saveexec_b64 s[40:41], vcc
	s_cbranch_execz .LBB0_1362
	v_cndmask_b32_e64 v89, v104, v161, s[8:9]
	v_lshlrev_b32_e32 v89, 6, v89
	v_and_b32_e32 v96, 0xfc0, v89
	v_mov_b32_e32 v97, v173
	v_lshl_add_u64 v[98:99], v[146:147], 0, v[96:97]
	v_lshl_add_u64 v[100:101], v[152:153], 0, v[96:97]
	global_load_dwordx2 v[96:97], v[98:99], off
	s_nop 0
	global_load_dwordx2 v[98:99], v[100:101], off
.LBB0_1362:
	s_or_b64 exec, exec, s[40:41]
	s_waitcnt vmcnt(0)
	v_pk_mul_f32 v[92:93], v[106:107], v[92:93] op_sel_hi:[0,1]
	v_pk_mul_f32 v[94:95], v[106:107], v[94:95] op_sel_hi:[0,1]
	v_pk_mul_f32 v[92:93], v[158:159], v[92:93]
	v_pk_mul_f32 v[94:95], v[156:157], v[94:95]
	v_pk_mul_f32 v[100:101], v[92:93], v[98:99]
	v_mov_b32_e32 v121, v173
	v_pk_fma_f32 v[100:101], v[94:95], v[96:97], v[100:101] neg_lo:[0,0,1] neg_hi:[0,0,1]
	v_pk_mul_f32 v[94:95], v[94:95], v[98:99]
	v_cvt_pk_bf16_f32 v89, v100, v101
	v_mov_b32_e32 v171, v170
	v_pk_fma_f32 v[92:93], v[92:93], v[96:97], v[94:95]
	v_lshlrev_b64 v[94:95], 10, v[104:105]
	v_lshl_add_u64 v[94:95], s[16:17], 0, v[94:95]
	v_lshl_add_u64 v[94:95], s[38:39], 1, v[94:95]
	v_lshl_add_u64 v[94:95], v[94:95], 0, v[120:121]
	global_store_dword v[94:95], v89, off
	v_cvt_pk_bf16_f32 v89, v92, v93
	global_store_dword v[94:95], v89, off offset:32
	ds_read_b128 v[94:97], v129 offset:768
	v_or_b32_e32 v92, 48, v166
	v_ashrrev_i32_e32 v93, 31, v92
	v_pk_mul_f32 v[76:77], v[76:77], v[170:171]
	v_cmp_gt_i32_e32 vcc, s83, v92
	s_waitcnt lgkmcnt(0)
	v_mov_b32_e32 v98, v95
	v_mov_b32_e32 v99, v96
	v_mov_b32_e32 v95, v97
	v_pk_add_f32 v[94:95], v[98:99], v[94:95]
	v_lshlrev_b64 v[98:99], 12, v[92:93]
	v_add_f32_e32 v89, v94, v95
	v_lshl_add_u64 v[94:95], v[92:93], 2, s[20:21]
	s_nop 2
	v_mov_b32_e32 v91, v242
	v_lshl_add_u64 v[98:99], s[14:15], 0, v[98:99]
	v_lshl_add_u64 v[98:99], s[36:37], 1, v[98:99]
	v_lshl_add_u64 v[98:99], v[98:99], 0, v[172:173]
	v_add_f32_e32 v89, v91, v89
	v_fmamk_f32 v89, v89, 0x3baaaaab, v189
	v_rsq_f32_e32 v94, v89
	v_mov_b32_e32 v89, 1.0
	v_mov_b32_e32 v91, 0
	v_mul_f32_e32 v96, v170, v94
	v_pk_mul_f32 v[84:85], v[84:85], v[96:97] op_sel_hi:[1,0]
	v_pk_mul_f32 v[86:87], v[86:87], v[96:97] op_sel_hi:[1,0]
	v_pk_mul_f32 v[80:81], v[80:81], v[96:97] op_sel_hi:[1,0]
	v_pk_mul_f32 v[82:83], v[82:83], v[96:97] op_sel_hi:[1,0]
	v_pk_mul_f32 v[86:87], v[70:71], v[86:87]
	v_pk_mul_f32 v[84:85], v[68:69], v[84:85]
	v_pk_mul_f32 v[96:97], v[66:67], v[82:83]
	v_pk_mul_f32 v[82:83], v[64:65], v[80:81]
	v_cvt_pk_bf16_f32 v80, v84, v85
	v_cvt_pk_bf16_f32 v81, v86, v87
	s_nop 0
	v_cvt_pk_bf16_f32 v82, v82, v83
	v_cvt_pk_bf16_f32 v83, v96, v97
	global_store_dwordx4 v[98:99], v[80:83], off
	s_nop 1
	v_mov_b32_e32 v80, v170
	v_mov_b32_e32 v81, v170
	v_pk_mul_f32 v[78:79], v[78:79], v[80:81]
	v_pk_mul_f32 v[80:81], v[74:75], v[80:81]
	v_pk_mul_f32 v[74:75], v[72:73], v[170:171]
	v_cvt_pk_bf16_f32 v72, v76, v77
	v_cvt_pk_bf16_f32 v73, v78, v79
	s_nop 0
	v_cvt_pk_bf16_f32 v74, v74, v75
	v_cvt_pk_bf16_f32 v75, v80, v81
	global_store_dwordx4 v[98:99], v[72:75], off offset:256
	s_nop 1
	v_mad_i64_i32 v[72:73], s[40:41], v92, s89, v[154:155]
	global_load_dwordx2 v[74:75], v[72:73], off offset:2560
	s_nop 0
	global_load_dwordx2 v[72:73], v[72:73], off offset:2624
	s_and_saveexec_b64 s[40:41], vcc
	s_cbranch_execz .LBB0_1364
	v_cndmask_b32_e64 v76, v92, v161, s[8:9]
	v_lshlrev_b32_e32 v76, 6, v76
	v_and_b32_e32 v76, 0xfc0, v76
	v_mov_b32_e32 v77, v173
	v_lshl_add_u64 v[78:79], v[146:147], 0, v[76:77]
	v_lshl_add_u64 v[76:77], v[152:153], 0, v[76:77]
	global_load_dwordx2 v[88:89], v[78:79], off
	global_load_dwordx2 v[90:91], v[76:77], off
; __device__ __forceinline__ unsigned cvt_pk_bf16(float lo, float hi) { unsigned r; asm volatile("v_cvt_pk_bf16_f32 %0, %1, %2" : "=v"(r) : "v"(lo), "v"(hi)); return r; }
; #define PG8_LAS __attribute__((address_space(3)))
;     __device__ __forceinline__ void operator()(const f32x4 (&acc)[2][2][4][2], const Unit& u, int wr, int wc, int fr, int fq) const {
;     ...
; #pragma unroll
;         for (int ai = 0; ai < 2; ++ai)
; #pragma unroll
;             for (int m = 0; m < 4; ++m) { const int row = row0 + ai * HALF + m * 16;
;                 const f32x4 p = *(const PG8_LAS f32x4*)(scr + (ai * HALF + rowl0 + m * 16) * 4);
;                 const float rinv = __builtin_amdgcn_rsqf((((p[0] + p[1]) + (p[2] + p[3])) + ssq_kp[row]) * (1.f / QKD) + EPS), ks = rl[ai][m] * rinv;
;                 bf16_t* kvp = KV + (size_t)row * (NH * 256) + h * 256 + colk;
;                 { const f32x4 k0 = acc[ai][0][m][0] * ks * g0, k1 = acc[ai][0][m][1] * ks * g1;
;                   u32x4 w; w.x = cvt_pk_bf16(k0[0], k0[1]); w.y = cvt_pk_bf16(k0[2], k0[3]); w.z = cvt_pk_bf16(k1[0], k1[1]); w.w = cvt_pk_bf16(k1[2], k1[3]); *(u32x4*)kvp = w; }
;                 { const f32x4 v0 = acc[ai][1][m][0] * rl[ai][m], v1 = acc[ai][1][m][1] * rl[ai][m];
;                   u32x4 w; w.x = cvt_pk_bf16(v0[0], v0[1]); w.y = cvt_pk_bf16(v0[2], v0[3]); w.z = cvt_pk_bf16(v1[0], v1[1]); w.w = cvt_pk_bf16(v1[2], v1[3]); *(u32x4*)(kvp + 128) = w; }
;                 const float* kp = QK + (size_t)row * NQKVA + (QLORA + KVLORA) + dA;
;                 const f32x2 ya = *(const f32x2*)kp * rinv * ga, yb = *(const f32x2*)(kp + 16) * rinv * gb;
;                 f32x2 cs = (f32x2){1.f, 1.f}, sn = (f32x2){0.f, 0.f};
;                 if (row < MLAT) { const int s = row & (SEQ - 1), pos = wc < 2 ? (s >> 6) : (s & 63); cs = *(const f32x2*)(rope + pos * 16 + ff); sn = *(const f32x2*)(rope + 1024 + pos * 16 + ff); }
;                 const f32x2 za = ya * cs - yb * sn, zb = yb * cs + ya * sn;
;                 bf16_t* pe = KPE + (size_t)row * (NH * QKR) + h * QKR + dA;
;                 *(unsigned*)pe = cvt_pk_bf16(za.x, za.y); *(unsigned*)(pe + 16) = cvt_pk_bf16(zb.x, zb.y); }
.LBB0_1364:
	s_or_b64 exec, exec, s[40:41]
	s_waitcnt vmcnt(0)
	v_pk_mul_f32 v[72:73], v[94:95], v[72:73] op_sel_hi:[0,1]
	v_pk_mul_f32 v[74:75], v[94:95], v[74:75] op_sel_hi:[0,1]
	v_pk_mul_f32 v[72:73], v[158:159], v[72:73]
	v_pk_mul_f32 v[74:75], v[156:157], v[74:75]
	v_pk_mul_f32 v[76:77], v[72:73], v[90:91]
	v_mov_b32_e32 v169, v168
	v_pk_fma_f32 v[76:77], v[74:75], v[88:89], v[76:77] neg_lo:[0,0,1] neg_hi:[0,0,1]
	v_pk_mul_f32 v[74:75], v[74:75], v[90:91]
	v_cvt_pk_bf16_f32 v76, v76, v77
	v_mov_b32_e32 v77, v168
	v_pk_fma_f32 v[72:73], v[72:73], v[88:89], v[74:75]
	v_lshlrev_b64 v[74:75], 10, v[92:93]
	v_lshl_add_u64 v[74:75], s[16:17], 0, v[74:75]
	v_lshl_add_u64 v[74:75], s[38:39], 1, v[74:75]
	v_lshl_add_u64 v[74:75], v[74:75], 0, v[120:121]
	global_store_dword v[74:75], v76, off
	v_cvt_pk_bf16_f32 v86, v72, v73
	s_nop 2
	v_mov_b32_e32 v87, v241
	v_mov_b32_e32 v76, v168
	v_pk_mul_f32 v[62:63], v[62:63], v[76:77]
	v_pk_mul_f32 v[76:77], v[54:55], v[76:77]
	v_pk_mul_f32 v[78:79], v[52:53], v[168:169]
	ds_read_b128 v[52:55], v129 offset:2048
	v_add_u32_e32 v72, 0x80, v166
	v_ashrrev_i32_e32 v73, 31, v72
	v_lshlrev_b64 v[82:83], 12, v[72:73]
	global_store_dword v[74:75], v86, off offset:32
	s_waitcnt lgkmcnt(0)
	v_mov_b32_e32 v84, v53
	v_mov_b32_e32 v85, v54
	v_mov_b32_e32 v53, v55
	v_pk_add_f32 v[52:53], v[84:85], v[52:53]
	v_lshl_add_u64 v[82:83], s[14:15], 0, v[82:83]
	v_add_f32_e32 v52, v52, v53
	v_lshl_add_u64 v[54:55], s[36:37], 1, v[82:83]
	v_lshl_add_u64 v[54:55], v[54:55], 0, v[172:173]
	v_pk_mul_f32 v[60:61], v[60:61], v[168:169]
	v_mad_i64_i32 v[80:81], s[40:41], v72, s89, v[154:155]
	s_movk_i32 s27, 0x3f80
	v_cmp_gt_i32_e32 vcc, s27, v166
	v_add_f32_e32 v52, v87, v52
	v_fmamk_f32 v52, v52, 0x3baaaaab, v189
	v_rsq_f32_e32 v52, v52
	s_nop 0
	v_mul_f32_e32 v74, v168, v52
	v_pk_mul_f32 v[48:49], v[48:49], v[74:75] op_sel_hi:[1,0]
	v_pk_mul_f32 v[50:51], v[50:51], v[74:75] op_sel_hi:[1,0]
	v_pk_mul_f32 v[56:57], v[56:57], v[74:75] op_sel_hi:[1,0]
	v_pk_mul_f32 v[58:59], v[58:59], v[74:75] op_sel_hi:[1,0]
	v_pk_mul_f32 v[74:75], v[66:67], v[50:51]
	v_pk_mul_f32 v[50:51], v[64:65], v[48:49]
	v_pk_mul_f32 v[58:59], v[70:71], v[58:59]
	v_pk_mul_f32 v[56:57], v[68:69], v[56:57]
	s_nop 0
	v_cvt_pk_bf16_f32 v48, v56, v57
	v_cvt_pk_bf16_f32 v49, v58, v59
	v_cvt_pk_bf16_f32 v50, v50, v51
	v_cvt_pk_bf16_f32 v51, v74, v75
	global_store_dwordx4 v[54:55], v[48:51], off
	v_mov_b32_e32 v58, 1.0
	v_mov_b32_e32 v59, 1.0
	v_cvt_pk_bf16_f32 v48, v60, v61
	v_cvt_pk_bf16_f32 v49, v62, v63
	v_cvt_pk_bf16_f32 v50, v78, v79
	v_cvt_pk_bf16_f32 v51, v76, v77
	global_store_dwordx4 v[54:55], v[48:51], off offset:256
	global_load_dwordx2 v[56:57], v[80:81], off offset:2560
	s_nop 0
	global_load_dwordx2 v[54:55], v[80:81], off offset:2624
	v_lshrrev_b32_e32 v62, 6, v72
	v_mov_b32_e32 v50, 0
	v_mov_b32_e32 v48, 1.0
	v_mov_b32_e32 v60, 0
	v_mov_b32_e32 v61, 0
	s_and_saveexec_b64 s[40:41], vcc
	s_cbranch_execz .LBB0_1366
	v_cndmask_b32_e64 v49, v145, v62, s[8:9]
	v_lshlrev_b32_e32 v49, 6, v49
	v_and_b32_e32 v58, 0xfc0, v49
	v_mov_b32_e32 v59, v173
	v_lshl_add_u64 v[60:61], v[146:147], 0, v[58:59]
	v_lshl_add_u64 v[74:75], v[152:153], 0, v[58:59]
	global_load_dwordx2 v[58:59], v[60:61], off
	s_nop 0
	global_load_dwordx2 v[60:61], v[74:75], off
.LBB0_1366:
	s_or_b64 exec, exec, s[40:41]
	s_waitcnt vmcnt(1)
	v_pk_mul_f32 v[56:57], v[52:53], v[56:57] op_sel_hi:[0,1]
	s_waitcnt vmcnt(0)
	v_pk_mul_f32 v[52:53], v[52:53], v[54:55] op_sel_hi:[0,1]
	v_pk_mul_f32 v[52:53], v[158:159], v[52:53]
	v_pk_mul_f32 v[56:57], v[156:157], v[56:57]
	v_pk_mul_f32 v[54:55], v[52:53], v[60:61]
	v_mov_b32_e32 v121, v173
	v_pk_fma_f32 v[54:55], v[56:57], v[58:59], v[54:55] neg_lo:[0,0,1] neg_hi:[0,0,1]
	v_pk_mul_f32 v[56:57], v[56:57], v[60:61]
	v_cvt_pk_bf16_f32 v49, v54, v55
	v_mov_b32_e32 v165, v164
	v_pk_fma_f32 v[52:53], v[52:53], v[58:59], v[56:57]
	v_lshlrev_b64 v[56:57], 10, v[72:73]
	v_lshl_add_u64 v[56:57], s[16:17], 0, v[56:57]
	v_lshl_add_u64 v[56:57], s[38:39], 1, v[56:57]
	v_lshl_add_u64 v[56:57], v[56:57], 0, v[120:121]
	global_store_dword v[56:57], v49, off
	v_cvt_pk_bf16_f32 v49, v52, v53
	global_store_dword v[56:57], v49, off offset:32
	ds_read_b128 v[54:57], v129 offset:2304
	v_or_b32_e32 v52, 16, v72
	v_ashrrev_i32_e32 v53, 31, v52
	v_pk_mul_f32 v[36:37], v[36:37], v[164:165]
	v_cmp_gt_i32_e32 vcc, s83, v52
	s_waitcnt lgkmcnt(0)
	v_mov_b32_e32 v58, v55
	v_mov_b32_e32 v59, v56
	v_mov_b32_e32 v55, v57
	v_pk_add_f32 v[54:55], v[58:59], v[54:55]
	v_lshlrev_b64 v[58:59], 12, v[52:53]
	v_add_f32_e32 v49, v54, v55
	v_lshl_add_u64 v[54:55], v[52:53], 2, s[20:21]
	s_nop 2
	v_mov_b32_e32 v51, v240
	v_lshl_add_u64 v[58:59], s[14:15], 0, v[58:59]
	v_lshl_add_u64 v[58:59], s[36:37], 1, v[58:59]
	v_lshl_add_u64 v[58:59], v[58:59], 0, v[172:173]
	v_add_f32_e32 v49, v51, v49
	v_fmamk_f32 v49, v49, 0x3baaaaab, v189
	v_rsq_f32_e32 v54, v49
	v_mov_b32_e32 v49, 1.0
	v_mov_b32_e32 v51, 0
	v_mul_f32_e32 v56, v164, v54
	v_pk_mul_f32 v[44:45], v[44:45], v[56:57] op_sel_hi:[1,0]
	v_pk_mul_f32 v[46:47], v[46:47], v[56:57] op_sel_hi:[1,0]
	v_pk_mul_f32 v[40:41], v[40:41], v[56:57] op_sel_hi:[1,0]
	v_pk_mul_f32 v[42:43], v[42:43], v[56:57] op_sel_hi:[1,0]
	v_pk_mul_f32 v[46:47], v[70:71], v[46:47]
	v_pk_mul_f32 v[44:45], v[68:69], v[44:45]
	v_pk_mul_f32 v[56:57], v[66:67], v[42:43]
	v_pk_mul_f32 v[42:43], v[64:65], v[40:41]
	v_cvt_pk_bf16_f32 v40, v44, v45
	v_cvt_pk_bf16_f32 v41, v46, v47
	s_nop 0
	v_cvt_pk_bf16_f32 v42, v42, v43
	v_cvt_pk_bf16_f32 v43, v56, v57
	global_store_dwordx4 v[58:59], v[40:43], off
	s_nop 1
	v_mov_b32_e32 v40, v164
	v_mov_b32_e32 v41, v164
	v_pk_mul_f32 v[38:39], v[38:39], v[40:41]
	v_pk_mul_f32 v[40:41], v[34:35], v[40:41]
	v_pk_mul_f32 v[34:35], v[32:33], v[164:165]
	v_cvt_pk_bf16_f32 v32, v36, v37
	v_cvt_pk_bf16_f32 v33, v38, v39
	s_nop 0
	v_cvt_pk_bf16_f32 v34, v34, v35
	v_cvt_pk_bf16_f32 v35, v40, v41
	global_store_dwordx4 v[58:59], v[32:35], off offset:256
	s_nop 1
	v_mad_i64_i32 v[32:33], s[40:41], v52, s89, v[154:155]
	global_load_dwordx2 v[34:35], v[32:33], off offset:2560
	s_nop 0
	global_load_dwordx2 v[32:33], v[32:33], off offset:2624
	s_and_saveexec_b64 s[40:41], vcc
	s_cbranch_execz .LBB0_1368
	v_cndmask_b32_e64 v36, v52, v62, s[8:9]
	v_lshlrev_b32_e32 v36, 6, v36
	v_and_b32_e32 v36, 0xfc0, v36
	v_mov_b32_e32 v37, v173
	v_lshl_add_u64 v[38:39], v[146:147], 0, v[36:37]
	v_lshl_add_u64 v[36:37], v[152:153], 0, v[36:37]
	global_load_dwordx2 v[48:49], v[38:39], off
	global_load_dwordx2 v[50:51], v[36:37], off
; __device__ __forceinline__ unsigned cvt_pk_bf16(float lo, float hi) { unsigned r; asm volatile("v_cvt_pk_bf16_f32 %0, %1, %2" : "=v"(r) : "v"(lo), "v"(hi)); return r; }
; #define PG8_LAS __attribute__((address_space(3)))
;     __device__ __forceinline__ void operator()(const f32x4 (&acc)[2][2][4][2], const Unit& u, int wr, int wc, int fr, int fq) const {
;     ...
; #pragma unroll
;         for (int ai = 0; ai < 2; ++ai)
; #pragma unroll
;             for (int m = 0; m < 4; ++m) { const int row = row0 + ai * HALF + m * 16;
;                 const f32x4 p = *(const PG8_LAS f32x4*)(scr + (ai * HALF + rowl0 + m * 16) * 4);
;                 const float rinv = __builtin_amdgcn_rsqf((((p[0] + p[1]) + (p[2] + p[3])) + ssq_kp[row]) * (1.f / QKD) + EPS), ks = rl[ai][m] * rinv;
;                 bf16_t* kvp = KV + (size_t)row * (NH * 256) + h * 256 + colk;
;                 { const f32x4 k0 = acc[ai][0][m][0] * ks * g0, k1 = acc[ai][0][m][1] * ks * g1;
;                   u32x4 w; w.x = cvt_pk_bf16(k0[0], k0[1]); w.y = cvt_pk_bf16(k0[2], k0[3]); w.z = cvt_pk_bf16(k1[0], k1[1]); w.w = cvt_pk_bf16(k1[2], k1[3]); *(u32x4*)kvp = w; }
;                 { const f32x4 v0 = acc[ai][1][m][0] * rl[ai][m], v1 = acc[ai][1][m][1] * rl[ai][m];
;                   u32x4 w; w.x = cvt_pk_bf16(v0[0], v0[1]); w.y = cvt_pk_bf16(v0[2], v0[3]); w.z = cvt_pk_bf16(v1[0], v1[1]); w.w = cvt_pk_bf16(v1[2], v1[3]); *(u32x4*)(kvp + 128) = w; }
;                 const float* kp = QK + (size_t)row * NQKVA + (QLORA + KVLORA) + dA;
;                 const f32x2 ya = *(const f32x2*)kp * rinv * ga, yb = *(const f32x2*)(kp + 16) * rinv * gb;
;                 f32x2 cs = (f32x2){1.f, 1.f}, sn = (f32x2){0.f, 0.f};
;                 if (row < MLAT) { const int s = row & (SEQ - 1), pos = wc < 2 ? (s >> 6) : (s & 63); cs = *(const f32x2*)(rope + pos * 16 + ff); sn = *(const f32x2*)(rope + 1024 + pos * 16 + ff); }
;                 const f32x2 za = ya * cs - yb * sn, zb = yb * cs + ya * sn;
;                 bf16_t* pe = KPE + (size_t)row * (NH * QKR) + h * QKR + dA;
;                 *(unsigned*)pe = cvt_pk_bf16(za.x, za.y); *(unsigned*)(pe + 16) = cvt_pk_bf16(zb.x, zb.y); }
.LBB0_1368:
	s_or_b64 exec, exec, s[40:41]
	s_waitcnt vmcnt(0)
	v_pk_mul_f32 v[32:33], v[54:55], v[32:33] op_sel_hi:[0,1]
	v_pk_mul_f32 v[34:35], v[54:55], v[34:35] op_sel_hi:[0,1]
	v_pk_mul_f32 v[32:33], v[158:159], v[32:33]
	v_pk_mul_f32 v[34:35], v[156:157], v[34:35]
	v_pk_mul_f32 v[36:37], v[32:33], v[50:51]
	v_mov_b32_e32 v163, v162
	v_pk_fma_f32 v[36:37], v[34:35], v[48:49], v[36:37] neg_lo:[0,0,1] neg_hi:[0,0,1]
	v_pk_mul_f32 v[34:35], v[34:35], v[50:51]
	v_cvt_pk_bf16_f32 v36, v36, v37
	v_pk_mul_f32 v[20:21], v[20:21], v[162:163]
	v_pk_fma_f32 v[32:33], v[32:33], v[48:49], v[34:35]
	v_lshlrev_b64 v[34:35], 10, v[52:53]
	v_lshl_add_u64 v[34:35], s[16:17], 0, v[34:35]
	v_lshl_add_u64 v[34:35], s[38:39], 1, v[34:35]
	v_lshl_add_u64 v[34:35], v[34:35], 0, v[120:121]
	global_store_dword v[34:35], v36, off
	v_cvt_pk_bf16_f32 v32, v32, v33
	global_store_dword v[34:35], v32, off offset:32
	ds_read_b128 v[34:37], v129 offset:2560
	v_or_b32_e32 v32, 32, v72
	v_ashrrev_i32_e32 v33, 31, v32
	v_cmp_gt_i32_e32 vcc, s83, v32
	s_waitcnt lgkmcnt(0)
	v_mov_b32_e32 v38, v35
	v_mov_b32_e32 v39, v36
	v_mov_b32_e32 v35, v37
	v_pk_add_f32 v[34:35], v[38:39], v[34:35]
	v_lshlrev_b64 v[38:39], 12, v[32:33]
	v_add_f32_e32 v36, v34, v35
	v_lshl_add_u64 v[34:35], v[32:33], 2, s[20:21]
	s_nop 2
	v_mov_b32_e32 v34, v239
	v_lshl_add_u64 v[38:39], s[14:15], 0, v[38:39]
	v_lshl_add_u64 v[38:39], s[36:37], 1, v[38:39]
	v_lshl_add_u64 v[38:39], v[38:39], 0, v[172:173]
	v_add_f32_e32 v34, v34, v36
	v_fmamk_f32 v34, v34, 0x3baaaaab, v189
	v_rsq_f32_e32 v34, v34
	s_nop 0
	v_mul_f32_e32 v36, v162, v34
	v_pk_mul_f32 v[28:29], v[28:29], v[36:37] op_sel_hi:[1,0]
	v_pk_mul_f32 v[30:31], v[30:31], v[36:37] op_sel_hi:[1,0]
	v_pk_mul_f32 v[24:25], v[24:25], v[36:37] op_sel_hi:[1,0]
	v_pk_mul_f32 v[26:27], v[26:27], v[36:37] op_sel_hi:[1,0]
	v_pk_mul_f32 v[30:31], v[70:71], v[30:31]
	v_pk_mul_f32 v[28:29], v[68:69], v[28:29]
	v_pk_mul_f32 v[36:37], v[66:67], v[26:27]
	v_pk_mul_f32 v[26:27], v[64:65], v[24:25]
	v_cvt_pk_bf16_f32 v24, v28, v29
	v_cvt_pk_bf16_f32 v25, v30, v31
	s_nop 0
	v_cvt_pk_bf16_f32 v26, v26, v27
	v_cvt_pk_bf16_f32 v27, v36, v37
	global_store_dwordx4 v[38:39], v[24:27], off
	s_nop 1
	v_mov_b32_e32 v24, v162
	v_mov_b32_e32 v25, v162
	v_pk_mul_f32 v[22:23], v[22:23], v[24:25]
	v_pk_mul_f32 v[24:25], v[18:19], v[24:25]
	v_pk_mul_f32 v[18:19], v[16:17], v[162:163]
	v_cvt_pk_bf16_f32 v16, v20, v21
	v_cvt_pk_bf16_f32 v17, v22, v23
	v_mov_b32_e32 v26, 0
	v_cvt_pk_bf16_f32 v18, v18, v19
	v_cvt_pk_bf16_f32 v19, v24, v25
	global_store_dwordx4 v[38:39], v[16:19], off offset:256
	v_mov_b32_e32 v24, 1.0
	v_mov_b32_e32 v25, 1.0
	v_mad_i64_i32 v[16:17], s[40:41], v32, s89, v[154:155]
	global_load_dwordx2 v[22:23], v[16:17], off offset:2560
	global_load_dwordx2 v[20:21], v[16:17], off offset:2624
	v_mov_b32_e32 v18, 0
	v_mov_b32_e32 v16, 1.0
	v_mov_b32_e32 v27, 0
	s_and_saveexec_b64 s[40:41], vcc
	s_cbranch_execz .LBB0_1370
	v_cndmask_b32_e64 v17, v32, v62, s[8:9]
	v_lshlrev_b32_e32 v17, 6, v17
	v_and_b32_e32 v24, 0xfc0, v17
	v_mov_b32_e32 v25, v173
	v_lshl_add_u64 v[26:27], v[146:147], 0, v[24:25]
	v_lshl_add_u64 v[28:29], v[152:153], 0, v[24:25]
	global_load_dwordx2 v[24:25], v[26:27], off
	s_nop 0
	global_load_dwordx2 v[26:27], v[28:29], off
.LBB0_1370:
	s_or_b64 exec, exec, s[40:41]
	s_waitcnt vmcnt(0)
	v_pk_mul_f32 v[20:21], v[34:35], v[20:21] op_sel_hi:[0,1]
	v_pk_mul_f32 v[22:23], v[34:35], v[22:23] op_sel_hi:[0,1]
	v_pk_mul_f32 v[20:21], v[158:159], v[20:21]
	v_pk_mul_f32 v[22:23], v[156:157], v[22:23]
	v_pk_mul_f32 v[28:29], v[20:21], v[26:27]
	v_mov_b32_e32 v121, v173
	v_pk_fma_f32 v[28:29], v[22:23], v[24:25], v[28:29] neg_lo:[0,0,1] neg_hi:[0,0,1]
	v_pk_mul_f32 v[22:23], v[22:23], v[26:27]
	v_cvt_pk_bf16_f32 v17, v28, v29
	v_mov_b32_e32 v161, v160
	v_pk_fma_f32 v[20:21], v[20:21], v[24:25], v[22:23]
	v_lshlrev_b64 v[22:23], 10, v[32:33]
	v_lshl_add_u64 v[22:23], s[16:17], 0, v[22:23]
	v_lshl_add_u64 v[22:23], s[38:39], 1, v[22:23]
	v_lshl_add_u64 v[22:23], v[22:23], 0, v[120:121]
	global_store_dword v[22:23], v17, off
	v_cvt_pk_bf16_f32 v17, v20, v21
	global_store_dword v[22:23], v17, off offset:32
	ds_read_b128 v[22:25], v129 offset:2816
	v_or_b32_e32 v20, 48, v72
	v_ashrrev_i32_e32 v21, 31, v20
	v_pk_mul_f32 v[4:5], v[4:5], v[160:161]
	v_cmp_gt_i32_e32 vcc, s83, v20
	s_waitcnt lgkmcnt(0)
	v_mov_b32_e32 v26, v23
	v_mov_b32_e32 v27, v24
	v_mov_b32_e32 v23, v25
	v_pk_add_f32 v[22:23], v[26:27], v[22:23]
	v_lshlrev_b64 v[26:27], 12, v[20:21]
	v_add_f32_e32 v17, v22, v23
	v_lshl_add_u64 v[22:23], v[20:21], 2, s[20:21]
	s_nop 2
	v_mov_b32_e32 v19, v238
	v_lshl_add_u64 v[26:27], s[14:15], 0, v[26:27]
	v_lshl_add_u64 v[26:27], s[36:37], 1, v[26:27]
	v_lshl_add_u64 v[26:27], v[26:27], 0, v[172:173]
	v_add_f32_e32 v17, v19, v17
	v_fmamk_f32 v17, v17, 0x3baaaaab, v189
	v_rsq_f32_e32 v22, v17
	v_mov_b32_e32 v17, 1.0
	v_mov_b32_e32 v19, 0
	v_mul_f32_e32 v24, v160, v22
	v_pk_mul_f32 v[12:13], v[12:13], v[24:25] op_sel_hi:[1,0]
	v_pk_mul_f32 v[14:15], v[14:15], v[24:25] op_sel_hi:[1,0]
	v_pk_mul_f32 v[8:9], v[8:9], v[24:25] op_sel_hi:[1,0]
	v_pk_mul_f32 v[10:11], v[10:11], v[24:25] op_sel_hi:[1,0]
	v_pk_mul_f32 v[14:15], v[70:71], v[14:15]
	v_pk_mul_f32 v[12:13], v[68:69], v[12:13]
	v_pk_mul_f32 v[24:25], v[66:67], v[10:11]
	v_pk_mul_f32 v[10:11], v[64:65], v[8:9]
	v_cvt_pk_bf16_f32 v8, v12, v13
	v_cvt_pk_bf16_f32 v9, v14, v15
	s_nop 0
	v_cvt_pk_bf16_f32 v10, v10, v11
	v_cvt_pk_bf16_f32 v11, v24, v25
	global_store_dwordx4 v[26:27], v[8:11], off
	s_nop 1
	v_mov_b32_e32 v8, v160
	v_mov_b32_e32 v9, v160
	v_pk_mul_f32 v[6:7], v[6:7], v[8:9]
	v_pk_mul_f32 v[8:9], v[2:3], v[8:9]
	v_pk_mul_f32 v[2:3], v[0:1], v[160:161]
	v_cvt_pk_bf16_f32 v0, v4, v5
	v_cvt_pk_bf16_f32 v1, v6, v7
	s_nop 0
	v_cvt_pk_bf16_f32 v2, v2, v3
	v_cvt_pk_bf16_f32 v3, v8, v9
	global_store_dwordx4 v[26:27], v[0:3], off offset:256
	s_nop 1
	v_mad_i64_i32 v[2:3], s[36:37], v20, s89, v[154:155]
	global_load_dwordx2 v[0:1], v[2:3], off offset:2560
	s_nop 0
	global_load_dwordx2 v[2:3], v[2:3], off offset:2624
	s_and_saveexec_b64 s[36:37], vcc
	s_cbranch_execz .LBB0_1372
	v_cndmask_b32_e64 v4, v20, v62, s[8:9]
	v_lshlrev_b32_e32 v4, 6, v4
	v_and_b32_e32 v4, 0xfc0, v4
	v_mov_b32_e32 v5, v173
	v_lshl_add_u64 v[6:7], v[146:147], 0, v[4:5]
	v_lshl_add_u64 v[4:5], v[152:153], 0, v[4:5]
	global_load_dwordx2 v[16:17], v[6:7], off
	global_load_dwordx2 v[18:19], v[4:5], off
